# tile order: FFN-up workgroups walk their 11 column tiles in descending order, so the hid columns the FFN-down K-loop reads first are the most recently written (cache resident)
# speedup vs baseline: 1.0073x; 1.0073x over previous
;     __host__ __device__ __forceinline__ bool next(int i, Unit& u) const {
;         const long L = (long)i * G + c; if (L >= nwg) return false;
;         int wgid = (int)L; { const int q = nwg / NXCD, r = nwg % NXCD, xcd = wgid % NXCD, off = wgid / NXCD; wgid = (xcd < r ? xcd * (q + 1) : r * (q + 1) + (xcd - r) * q) + off; }
;         const int nig = WGM * nN, gid = wgid / nig, fm = gid * WGM, gsz = (nM - fm) < WGM ? (nM - fm) : WGM;
;         u.pm = fm + ((wgid % nig) % gsz); u.pn = (wgid % nig) / gsz; return true;
.LBB0_125:
	v_readlane_b32 s0, v254, 16
	v_readlane_b32 s1, v254, 17
	s_andn2_b64 vcc, exec, s[0:1]
	s_cbranch_vccnz .LBB0_224
	v_mov_b32_e32 v72, v0
	v_readlane_b32 s28, v254, 0
	v_readlane_b32 s4, v254, 11
	s_ashr_i32 s30, s28, 31
	v_readlane_b32 s6, v254, 13
	v_readlane_b32 s7, v254, 14
	s_cmpk_lt_i32 s28, 0xb00
	v_readlane_b32 s29, v254, 3
	s_mov_b64 s[0:1], 0
	s_mov_b32 s24, s4
	s_cselect_b64 s[6:7], -1, 0
	s_cmpk_gt_i32 s28, 0xaff
	v_readlane_b32 s5, v254, 12
	s_cbranch_scc1 .LBB0_128
	s_mov_b32 s9, s28
	s_cmp_lg_u32 s29, 0x100
	s_cbranch_scc1 .Lrev0_u1
	s_add_i32 s9, s28, 0xa00
.Lrev0_u1:
	s_ashr_i32 s8, s9, 31
	s_lshr_b32 s4, s8, 29
	s_add_i32 s4, s9, s4
	s_ashr_i32 s5, s4, 3
	s_and_b32 s4, s4, -8
	s_sub_i32 s4, s9, s4
	s_cmp_lt_i32 s4, 0
	s_cselect_b32 s8, s88, 0x160
	s_mul_i32 s4, s4, s8
	s_add_i32 s4, s4, s5
	s_mul_hi_i32 s5, s4, 0x2e8ba2e9
	s_lshr_b32 s8, s5, 31
	s_ashr_i32 s5, s5, 6
	s_add_i32 s5, s5, s8
	s_lshl_b32 s8, s5, 3
	s_mulk_i32 s5, 0x160
	s_sub_i32 s4, s4, s5
	s_bfe_u32 s5, s4, 0x3001c
	s_add_i32 s5, s4, s5
	s_and_b32 s9, s5, 0xfff8
	s_sub_i32 s4, s4, s9
	s_sext_i32_i16 s4, s4
	s_add_i32 s4, s8, s4
	v_writelane_b32 v254, s4, 52
	s_nop 1
	v_writelane_b32 v254, s5, 53
	s_sext_i32_i16 s4, s5
	s_ashr_i32 s4, s4, 3
	v_writelane_b32 v255, s4, 2

; #define PG8_WAIT_V(n) asm volatile("s_waitcnt vmcnt(" #n ")" ::: "memory")
; #define PG8_BAR __builtin_amdgcn_s_barrier()
;     __host__ __device__ __forceinline__ bool next(int i, Unit& u) const {
;         const long L = (long)i * G + c; if (L >= nwg) return false;
;         int wgid = (int)L; { const int q = nwg / NXCD, r = nwg % NXCD, xcd = wgid % NXCD, off = wgid / NXCD; wgid = (xcd < r ? xcd * (q + 1) : r * (q + 1) + (xcd - r) * q) + off; }
;         const int nig = WGM * nN, gid = wgid / nig, fm = gid * WGM, gsz = (nM - fm) < WGM ? (nM - fm) : WGM;
;         u.pm = fm + ((wgid % nig) % gsz); u.pn = (wgid % nig) / gsz; return true;
;     ...
;     unsigned voffA[2], voffB[2];
; #pragma unroll
;     for (int i = 0; i < 2; ++i) { int R, C; stage_rc(tid * 16 + i * 8192, R, C); const int Rb = Epi::PERM ? ((R & ~31) + perm32(R & 31)) : R;
;         voffA[i] = A_TILED ? (unsigned)(R * BK + C) * 2u : (unsigned)(R * K + C) * 2u; voffB[i] = (unsigned)(Rb * BK + C) * 2u; }
;     const size_t kstep = A_TILED ? (size_t)BM * BK * 2 : (size_t)(BK * 2);
;     const size_t hstep = A_TILED ? (size_t)HALF * BK * 2 : (size_t)HALF * K * 2;
;     const size_t tstep = (size_t)BM * K * 2;
;     const size_t kstepB = (size_t)BM * BK * 2, hstepB = (size_t)HALF * BK * 2;
;     const unsigned ldsw = (unsigned)wid * 1024u;
;     const int aoff = lds_byte(wr * 64 + fr, fq * 8), boff = lds_byte(wc * 32 + fr, fq * 8);
;     ...
;     Unit cur, nxt; int ui = 0;
;     if (!S.next(0, cur)) return;
;     acc_t acc[2][2][4][2];
; #pragma unroll
;     for (int a = 0; a < 2; ++a)
; #pragma unroll
;         for (int b = 0; b < 2; ++b)
; #pragma unroll
;             for (int m = 0; m < 4; ++m)
; #pragma unroll
;                 for (int n = 0; n < 2; ++n) acc[a][b][m][n] = acc_t{};
;     frag_t At[4][2], B0[2][2], B1[2][2];
;     const char* cA = (const char*)g.A + (size_t)cur.pm * tstep; const char* cB = (const char*)g.Bt + (size_t)cur.pn * tstep;
;     S.a_ready(cur);
;     if constexpr (SP2) {
;         PG8_STAGE(PG8_SB(0, 0), cB, voffB); PG8_STAGE(PG8_SB(0, 1), cB + hstepB, voffB); PG8_STAGE(PG8_SA(0, 0), cA, voffA); PG8_STAGE(PG8_SA(0, 1), cA + hstep, voffA);
;         if (wr == 1) PG8_BAR;
;         PG8_WAIT_V(2); PG8_BAR;
;         PG8_STAGE(PG8_SB(1, 0), cB + kstepB, voffB); PG8_STAGE(PG8_SA(1, 0), cA + kstep, voffA); PG8_STAGE(PG8_SB(1, 1), cB + hstepB + kstepB, voffB);
.LBB0_154:
	s_and_b64 vcc, exec, s[4:5]
	v_readfirstlane_b32 s12, v72
	s_cbranch_vccnz .LBB0_170
	s_waitcnt lgkmcnt(0)
	v_lshlrev_b32_e32 v1, 4, v72
	v_add_u32_e32 v2, 0x2000, v1
	v_ashrrev_i32_e32 v3, 31, v2
	v_lshrrev_b32_e32 v3, 22, v3
	v_add_u32_e32 v3, v2, v3
	s_waitcnt vmcnt(0)
	v_ashrrev_i32_e32 v6, 10, v3
	v_mul_i32_i24_e32 v3, 0x400, v6
	v_sub_u32_e32 v2, v2, v3
	v_lshrrev_b32_e32 v3, 4, v2
	v_bitop3_b32 v2, v3, v2, 32 bitop3:0x6c
	s_ashr_i32 s13, s12, 6
	v_ashrrev_i32_e32 v3, 31, v2
	s_lshl_b32 s14, s24, 1
	s_ashr_i32 s5, s12, 8
	s_lshl_b32 s31, s13, 10
	s_mul_i32 s24, s24, 0x5800000
	v_lshrrev_b32_e32 v3, 26, v3
	s_mul_hi_i32 s4, s14, 0x2c00000
	s_add_u32 s6, s10, s24
	v_add_u32_e32 v3, v2, v3
	v_lshlrev_b32_e32 v4, 3, v6
	s_addc_u32 s4, s11, s4
	v_ashrrev_i32_e32 v7, 6, v3
	v_and_b32_e32 v4, -16, v4
	s_add_u32 s34, s6, 0x800000
	v_add_u32_e32 v4, v7, v4
	s_addc_u32 s35, s4, 0
	v_and_b32_e32 v5, 3, v7
	s_mov_b32 s4, 0x1ffffe0
	v_lshrrev_b32_e32 v8, 2, v4
	v_lshlrev_b32_e32 v9, 1, v4
	v_and_b32_e32 v3, 0xc0, v3
	v_and_or_b32 v5, v4, s4, v5
	v_and_b32_e32 v8, 4, v8
	v_and_b32_e32 v9, 24, v9
	v_sub_u32_e32 v2, v2, v3
	v_or3_b32 v5, v5, v8, v9
	v_lshlrev_b32_e32 v8, 5, v6
	v_ashrrev_i16_sdwa v2, v194, sext(v2) dst_sel:DWORD dst_unused:UNUSED_PAD src0_sel:DWORD src1_sel:BYTE_0
	v_and_b32_e32 v9, 32, v8
	v_bfe_i32 v8, v2, 0, 16
	v_add_lshl_u32 v2, v9, v8, 1
	v_lshl_add_u32 v130, v5, 7, v2
	v_lshl_add_u32 v132, v4, 11, v2
	v_bfe_i32 v2, v72, 27, 1
	v_lshrrev_b32_e32 v2, 22, v2
	v_add_u32_e32 v2, v1, v2
	v_and_b32_e32 v2, 0xfffffc00, v2
	v_sub_u32_e32 v1, v1, v2
	v_lshrrev_b32_e32 v2, 4, v1
	v_ashrrev_i32_e32 v3, 31, v72
	v_bitop3_b32 v1, v2, v1, 32 bitop3:0x6c
	v_lshrrev_b32_e32 v3, 26, v3
	v_ashrrev_i32_e32 v2, 31, v1
	v_add_u32_e32 v3, v72, v3
	v_lshrrev_b32_e32 v2, 26, v2
	v_ashrrev_i32_e32 v10, 6, v3
	v_add_u32_e32 v2, v1, v2
	v_lshlrev_b32_e32 v3, 3, v10
	v_ashrrev_i32_e32 v9, 6, v2
	v_and_b32_e32 v3, -16, v3
	v_add_u32_e32 v3, v9, v3
	v_and_b32_e32 v4, 3, v9
	v_and_or_b32 v4, v3, s4, v4
	v_readlane_b32 s7, v254, 3
	s_nop 1
	s_cmp_lg_u32 s7, 0x100
	s_mov_b32 s7, s28
	s_cbranch_scc1 .LrevG_1
	s_add_i32 s7, s28, 0xa00
.LrevG_1:
	s_ashr_i32 s4, s7, 31
	s_lshr_b32 s4, s4, 29
	s_add_i32 s4, s7, s4
	s_ashr_i32 s6, s4, 3
	s_and_b32 s4, s4, -8
	s_sub_i32 s4, s7, s4
	s_cmp_lt_i32 s4, 0
	s_cselect_b32 s7, s88, 0x160
	s_mul_i32 s4, s4, s7
	s_add_i32 s4, s4, s6
	s_mul_hi_i32 s6, s4, 0x2e8ba2e9
	s_lshr_b32 s7, s6, 31
	s_ashr_i32 s6, s6, 6
	s_add_i32 s6, s6, s7
	s_lshl_b32 s7, s6, 3
	s_mulk_i32 s6, 0x160
	s_sub_i32 s6, s4, s6
	s_bfe_u32 s4, s6, 0x3001c
	s_add_i32 s8, s6, s4
	s_sext_i32_i16 s4, s8
	s_and_b32 s8, s8, 0xfff8
	s_sub_i32 s6, s6, s8
	s_sext_i32_i16 s6, s6
	v_lshrrev_b32_e32 v5, 2, v3
	v_lshlrev_b32_e32 v11, 1, v3
	v_and_b32_e32 v2, 0xc0, v2
	s_lshr_b32 s4, s4, 3
	s_add_i32 s20, s7, s6
	v_and_b32_e32 v5, 4, v5
	v_and_b32_e32 v11, 24, v11
	v_sub_u32_e32 v1, v1, v2
	s_ashr_i32 s21, s20, 31
	s_bfe_i64 s[8:9], s[4:5], 0x100000
	v_or3_b32 v4, v4, v5, v11
	v_lshlrev_b32_e32 v5, 5, v10
	v_ashrrev_i16_sdwa v1, v194, sext(v1) dst_sel:DWORD dst_unused:UNUSED_PAD src0_sel:DWORD src1_sel:BYTE_0
	s_lshl_b64 s[6:7], s[20:21], 19
	s_lshl_b64 s[8:9], s[8:9], 19
	v_and_b32_e32 v5, 32, v5
	v_bfe_i32 v11, v1, 0, 16
	s_add_u32 s22, s34, s8
	v_add_lshl_u32 v1, v5, v11, 1
	s_addc_u32 s23, s35, s9
	s_add_i32 s36, s31, 0
	v_lshl_add_u32 v134, v4, 7, v1
	s_add_i32 m0, s36, 0x10000
	v_lshl_add_u32 v136, v3, 11, v1
	global_load_lds_dwordx4 v134, s[22:23]
	s_add_i32 m0, s36, 0x12000
	s_add_u32 s8, s22, 0x4000
	global_load_lds_dwordx4 v130, s[22:23]
	s_addc_u32 s9, s23, 0
	s_add_i32 m0, s36, 0x14000
	v_mov_b32_e32 v137, v163
	global_load_lds_dwordx4 v134, s[8:9]
	s_add_i32 m0, s36, 0x16000
	s_add_u32 s24, s0, s6
	s_addc_u32 s25, s1, s7
	s_add_i32 s37, s36, 0x2000
	global_load_lds_dwordx4 v130, s[8:9]
	s_mov_b32 m0, s36
	s_add_u32 s6, s24, 0x40000
	global_load_lds_dwordx4 v136, s[24:25]
	s_mov_b32 m0, s37
	s_addc_u32 s7, s25, 0
	s_add_i32 s38, s36, 0x4000
	global_load_lds_dwordx4 v132, s[24:25]
	s_mov_b32 m0, s38
	s_add_i32 s39, s36, 0x6000
	global_load_lds_dwordx4 v136, s[6:7]
	s_mov_b32 m0, s39
	v_mov_b32_e32 v133, v163
	global_load_lds_dwordx4 v132, s[6:7]
	s_cmp_eq_u32 s5, 1
	v_lshl_add_u64 v[2:3], s[24:25], 0, v[136:137]
	s_cselect_b64 s[6:7], -1, 0
	s_cmp_lg_u32 s5, 1
	v_lshl_add_u64 v[4:5], s[24:25], 0, v[132:133]
	s_cbranch_scc1 .LBB0_157
	s_barrier
; #define PG8_STAGE(bufoff, gbase, voff) do { _Pragma("unroll") for (int _i = 0; _i < 2; ++_i) \
;         __builtin_amdgcn_global_load_lds((const unsigned*)((const char*)(gbase) + (voff)[_i]), (PG8_LAS unsigned*)(lds + (bufoff) + ldsw + _i * 8192), 16, 0, 0); } while (0)
; #define PG8_WAIT_V(n) asm volatile("s_waitcnt vmcnt(" #n ")" ::: "memory")
; #define PG8_BAR __builtin_amdgcn_s_barrier()
;     ...
;         PG8_STAGE(PG8_SB(1, 0), cB + kstepB, voffB); PG8_STAGE(PG8_SA(1, 0), cA + kstep, voffA); PG8_STAGE(PG8_SB(1, 1), cB + hstepB + kstepB, voffB);
;         PG8_WAIT_V(6); PG8_BAR;
;     __device__ __forceinline__ void operator()(const i32x4 (&acc)[2][2][4][2], const pg8::Unit& u, int wr, int wc, int fr_, int fq_, int tid) {
;     ...
;         const float* cp = cmax + u.pn * 256 + wc * 32 + 8 * fq;
;         f32x4 cs[2][2];
;         cs[0][0] = *(const f32x4*)(cp) * (1.0f / 127.0f); cs[0][1] = *(const f32x4*)(cp + 4) * (1.0f / 127.0f);
;         cs[1][0] = *(const f32x4*)(cp + 128) * (1.0f / 127.0f); cs[1][1] = *(const f32x4*)(cp + 132) * (1.0f / 127.0f);
.LBB0_157:
	s_add_u32 s8, s10, 0x2d800000
	s_addc_u32 s9, s11, 0
	s_mul_hi_i32 s15, s14, 0xb000
	s_mul_i32 s14, s14, 0xb000
	s_add_u32 s14, s10, s14
	s_addc_u32 s15, s11, s15
	s_lshl_b32 s10, s13, 5
	s_and_b32 s41, s10, 0x60
	s_lshl_b32 s40, s5, 6
	s_lshl_b32 s16, s5, 13
	s_lshl_b32 s13, s41, 7
	s_add_u32 s10, s22, 0x8000
	v_mov_b32_e32 v135, v163
	s_addc_u32 s11, s23, 0
	v_mov_b32_e32 v131, v163
	s_add_i32 m0, s36, 0x18000
	v_lshl_add_u64 v[12:13], s[10:11], 0, v[134:135]
	s_waitcnt vmcnt(2)
	s_barrier
	global_load_lds_dwordx4 v[12:13], off
	v_lshl_add_u64 v[12:13], s[10:11], 0, v[130:131]
	s_add_i32 m0, s36, 0x1a000
	s_add_i32 s42, s36, 0x8000
	s_add_i32 s43, s36, 0xa000
	global_load_lds_dwordx4 v[12:13], off
	v_lshl_add_u64 v[2:3], v[2:3], 0, s[78:79]
	s_mov_b32 m0, s42
	s_add_u32 s10, s22, 0xc000
	global_load_lds_dwordx4 v[2:3], off
	v_lshl_add_u64 v[2:3], v[4:5], 0, s[78:79]
	s_mov_b32 m0, s43
	s_addc_u32 s11, s23, 0
	global_load_lds_dwordx4 v[2:3], off
	s_add_i32 m0, s36, 0x1c000
	v_lshl_add_u64 v[2:3], s[10:11], 0, v[134:135]
	global_load_lds_dwordx4 v[2:3], off
	v_lshl_add_u64 v[2:3], s[10:11], 0, v[130:131]
	s_add_i32 m0, s36, 0x1e000
	v_bfe_u32 v155, v72, 4, 2
	global_load_lds_dwordx4 v[2:3], off
	v_and_b32_e32 v1, 15, v72
	v_lshlrev_b32_e32 v2, 4, v155
	v_lshlrev_b32_e32 v3, 2, v72
	v_lshl_or_b32 v2, v1, 6, v2
	v_and_b32_e32 v3, 32, v3
	v_bitop3_b32 v4, v2, s16, v3 bitop3:0xde
	v_bitop3_b32 v158, s13, v2, v3 bitop3:0xf6
	v_lshlrev_b32_e32 v2, 14, v10
	s_cmpk_lt_u32 s12, 0x100
	v_and_b32_e32 v2, 0xffff8000, v2
	s_sext_i32_i16 s21, s4
	s_cselect_b64 s[10:11], -1, 0
	s_ashr_i32 s44, s29, 31
	s_lshl_b32 s4, s41, 2
	v_lshl_add_u32 v2, v9, 11, v2
	v_and_b32_e32 v3, 1, v10
	s_add_u32 s4, s14, s4
	v_lshl_or_b32 v2, v3, 6, v2
	s_addc_u32 s12, s15, 0
	v_lshl_add_u32 v138, v11, 1, v2
	v_lshlrev_b32_e32 v2, 14, v6
	s_add_u32 s45, s4, 0x80000
	v_and_b32_e32 v2, 0xffff8000, v2
	s_waitcnt vmcnt(6)
	s_addc_u32 s46, s12, 0
	s_lshl_b32 s4, s5, 8
	v_lshl_add_u32 v2, v7, 11, v2
	v_and_b32_e32 v3, 1, v6
	s_add_i32 s47, s4, 0
	v_lshl_or_b32 v2, v3, 6, v2
	s_add_i32 s47, s47, 0x20400
	v_mov_b32_e32 v139, v163
	v_lshl_add_u32 v140, v8, 1, v2
	v_mov_b32_e32 v141, v163
	s_mov_b32 s48, 0
	v_add_u32_e32 v159, 0, v4
	v_and_b32_e32 v216, 31, v195
	v_lshrrev_b32_e32 v217, 5, v195
	v_lshl_add_u32 v216, v217, 7, v216
	v_lshlrev_b32_e32 v216, 2, v216
	s_and_b32 s96, s21, 3
	s_lshl_b32 s96, s96, 10
	s_add_u32 s100, s45, s96
	s_addc_u32 s101, s46, 0
	global_load_dword v220, v216, s[100:101]
	s_add_u32 s100, s100, 0x1000
	s_addc_u32 s101, s101, 0
	global_load_dword v221, v216, s[100:101]
	s_add_u32 s100, s100, 0x1000
	s_addc_u32 s101, s101, 0
	global_load_dword v222, v216, s[100:101]
	s_add_u32 s100, s100, 0x1000
	s_addc_u32 s101, s101, 0
	global_load_dword v223, v216, s[100:101]
	s_add_u32 s100, s100, 0x1000
	s_addc_u32 s101, s101, 0
	global_load_dword v224, v216, s[100:101]
	s_add_u32 s100, s100, 0x1000
	s_addc_u32 s101, s101, 0
	global_load_dword v225, v216, s[100:101]
	s_add_u32 s100, s100, 0x1000
	s_addc_u32 s101, s101, 0
	global_load_dword v226, v216, s[100:101]
	s_add_u32 s100, s100, 0x1000
	s_addc_u32 s101, s101, 0
	global_load_dword v227, v216, s[100:101]
	s_add_u32 s100, s100, 0x1000
	s_addc_u32 s101, s101, 0
	global_load_dword v228, v216, s[100:101]
	s_add_u32 s100, s100, 0x1000
	s_addc_u32 s101, s101, 0
	global_load_dword v229, v216, s[100:101]
	s_add_u32 s100, s100, 0x1000
	s_addc_u32 s101, s101, 0
	global_load_dword v230, v216, s[100:101]
	s_lshl_b32 s96, s41, 3
	s_add_i32 s96, s96, 0x21000
	v_lshl_add_u32 v217, v195, 2, s96
	s_waitcnt vmcnt(0)
	v_mul_f32_e32 v220, s76, v220
	v_mul_f32_e32 v221, s76, v221
	v_mul_f32_e32 v222, s76, v222
	v_mul_f32_e32 v223, s76, v223
	v_mul_f32_e32 v224, s76, v224
	v_mul_f32_e32 v225, s76, v225
	v_mul_f32_e32 v226, s76, v226
	v_mul_f32_e32 v227, s76, v227
	v_mul_f32_e32 v228, s76, v228
	v_mul_f32_e32 v229, s76, v229
	v_mul_f32_e32 v230, s76, v230
	ds_write_b32 v217, v220
	ds_write_b32 v217, v221 offset:1024
	ds_write_b32 v217, v222 offset:2048
	ds_write_b32 v217, v223 offset:3072
	ds_write_b32 v217, v224 offset:4096
	ds_write_b32 v217, v225 offset:5120
	ds_write_b32 v217, v226 offset:6144
	ds_write_b32 v217, v227 offset:7168
	ds_write_b32 v217, v228 offset:8192
	ds_write_b32 v217, v229 offset:9216
	ds_write_b32 v217, v230 offset:10240
	s_waitcnt lgkmcnt(0)
	s_barrier
	s_branch .LBB0_160

;     __host__ __device__ __forceinline__ bool next(int i, Unit& u) const {
;         const long L = (long)i * G + c; if (L >= nwg) return false;
;         int wgid = (int)L; { const int q = nwg / NXCD, r = nwg % NXCD, xcd = wgid % NXCD, off = wgid / NXCD; wgid = (xcd < r ? xcd * (q + 1) : r * (q + 1) + (xcd - r) * q) + off; }
;         const int nig = WGM * nN, gid = wgid / nig, fm = gid * WGM, gsz = (nM - fm) < WGM ? (nM - fm) : WGM;
;         u.pm = fm + ((wgid % nig) % gsz); u.pn = (wgid % nig) / gsz; return true;
;     ...
;         const bool has_next = S.next(ui + 1, nxt);
.LBB0_160:
	s_add_i32 s48, s48, 1
	s_mul_i32 s4, s48, s44
	s_mul_hi_u32 s5, s48, s29
	s_add_i32 s5, s5, s4
	s_mul_i32 s4, s48, s29
	s_add_u32 s16, s4, s28
	s_addc_u32 s17, s5, s30
	v_cmp_gt_i64_e32 vcc, s[16:17], v[166:167]
	v_cmp_lt_i64_e64 s[4:5], s[16:17], v[164:165]
	s_cbranch_vccnz .LBB0_162
	s_cmp_lg_u32 s29, 0x100
	s_cbranch_scc1 .Lrev_u1
	s_lshl_b32 s12, s28, 1
	s_add_i32 s12, s12, 0xa00
	s_sub_i32 s16, s12, s16
.Lrev_u1:
	s_ashr_i32 s12, s16, 31
	s_lshr_b32 s12, s12, 29
	s_add_i32 s12, s16, s12
	s_ashr_i32 s13, s12, 3
	s_and_b32 s12, s12, -8
	s_sub_i32 s12, s16, s12
	s_cmp_lt_i32 s12, 0
	s_cselect_b32 s14, s88, 0x160
	s_mul_i32 s12, s12, s14
	s_add_i32 s12, s12, s13
	s_mul_hi_i32 s13, s12, 0x2e8ba2e9
	s_lshr_b32 s14, s13, 31
	s_ashr_i32 s13, s13, 6
	s_add_i32 s13, s13, s14
	s_lshl_b32 s14, s13, 3
	s_sub_i32 s15, 64, s14
	s_min_i32 s15, s15, 8
	s_abs_i32 s16, s15
	v_cvt_f32_u32_e32 v2, s16
	s_sub_i32 s18, 0, s16
	s_mulk_i32 s13, 0x160
	s_sub_i32 s13, s12, s13
	v_rcp_iflag_f32_e32 v2, v2
	s_abs_i32 s12, s13
	s_xor_b32 s17, s13, s15
	s_ashr_i32 s17, s17, 31
	v_mul_f32_e32 v2, 0x4f7ffffe, v2
	v_cvt_u32_f32_e32 v2, v2
	s_nop 0
	v_readfirstlane_b32 s19, v2
	s_mul_i32 s18, s18, s19
	s_mul_hi_u32 s18, s19, s18
	s_add_i32 s19, s19, s18
	s_mul_hi_u32 s18, s12, s19
	s_mul_i32 s19, s18, s16
	s_sub_i32 s12, s12, s19
	s_add_i32 s26, s18, 1
	s_sub_i32 s19, s12, s16
	s_cmp_ge_u32 s12, s16
	s_cselect_b32 s18, s26, s18
	s_cselect_b32 s12, s19, s12
	s_add_i32 s19, s18, 1
	s_cmp_ge_u32 s12, s16
	s_cselect_b32 s12, s19, s18
	s_xor_b32 s12, s12, s17
	s_sub_i32 s12, s12, s17
	s_mul_i32 s15, s12, s15
	s_sub_i32 s13, s13, s15
	s_add_i32 s14, s14, s13

;     __host__ __device__ __forceinline__ bool next(int i, Unit& u) const {
;         const long L = (long)i * G + c; if (L >= nwg) return false;
;         int wgid = (int)L; { const int q = nwg / NXCD, r = nwg % NXCD, xcd = wgid % NXCD, off = wgid / NXCD; wgid = (xcd < r ? xcd * (q + 1) : r * (q + 1) + (xcd - r) * q) + off; }
;         const int nig = WGM * nN, gid = wgid / nig, fm = gid * WGM, gsz = (nM - fm) < WGM ? (nM - fm) : WGM;
;         u.pm = fm + ((wgid % nig) % gsz); u.pn = (wgid % nig) / gsz; return true;
.LBB0_1101:
	v_readlane_b32 s0, v254, 38
	v_readlane_b32 s1, v254, 39
	s_andn2_b64 vcc, exec, s[0:1]
	s_cbranch_vccnz .LBB0_1200
	v_mov_b32_e32 v70, v0
	v_readlane_b32 s28, v254, 0
	v_readlane_b32 s4, v254, 11
	s_ashr_i32 s30, s28, 31
	v_readlane_b32 s6, v254, 13
	v_readlane_b32 s7, v254, 14
	s_cmpk_lt_i32 s28, 0xb00
	v_readlane_b32 s29, v254, 3
	s_mov_b64 s[0:1], 0
	s_cselect_b64 s[6:7], -1, 0
	s_cmpk_gt_i32 s28, 0xaff
	v_readlane_b32 s5, v254, 12
	s_cbranch_scc1 .LBB0_1104
	s_mov_b32 s10, s28
	s_cmp_lg_u32 s29, 0x100
	s_cbranch_scc1 .Lrev0_u2
	s_add_i32 s10, s28, 0xa00
.Lrev0_u2:
	s_ashr_i32 s9, s10, 31
	s_lshr_b32 s5, s9, 29
	s_add_i32 s5, s10, s5
	s_ashr_i32 s8, s5, 3
	s_and_b32 s5, s5, -8
	s_sub_i32 s5, s10, s5
	s_cmp_lt_i32 s5, 0
	s_cselect_b32 s9, s88, 0x160
	s_mul_i32 s5, s5, s9
	s_add_i32 s5, s5, s8
	s_mul_hi_i32 s8, s5, 0x2e8ba2e9
	s_lshr_b32 s9, s8, 31
	s_ashr_i32 s8, s8, 6
	s_add_i32 s8, s8, s9
	s_lshl_b32 s9, s8, 3
	s_mulk_i32 s8, 0x160
	s_sub_i32 s5, s5, s8
	s_bfe_u32 s8, s5, 0x3001c
	s_add_i32 s8, s5, s8
	s_and_b32 s10, s8, 0xfff8
	s_sub_i32 s5, s5, s10
	s_sext_i32_i16 s5, s5
	s_add_i32 s10, s9, s5
	s_sext_i32_i16 s5, s8
	v_writelane_b32 v254, s10, 54
	s_ashr_i32 s5, s5, 3
	v_writelane_b32 v255, s5, 21
	v_writelane_b32 v254, s11, 55

; #define PG8_WAIT_V(n) asm volatile("s_waitcnt vmcnt(" #n ")" ::: "memory")
; #define PG8_BAR __builtin_amdgcn_s_barrier()
;     __host__ __device__ __forceinline__ bool next(int i, Unit& u) const {
;         const long L = (long)i * G + c; if (L >= nwg) return false;
;         int wgid = (int)L; { const int q = nwg / NXCD, r = nwg % NXCD, xcd = wgid % NXCD, off = wgid / NXCD; wgid = (xcd < r ? xcd * (q + 1) : r * (q + 1) + (xcd - r) * q) + off; }
;         const int nig = WGM * nN, gid = wgid / nig, fm = gid * WGM, gsz = (nM - fm) < WGM ? (nM - fm) : WGM;
;         u.pm = fm + ((wgid % nig) % gsz); u.pn = (wgid % nig) / gsz; return true;
;     ...
;     unsigned voffA[2], voffB[2];
; #pragma unroll
;     for (int i = 0; i < 2; ++i) { int R, C; stage_rc(tid * 16 + i * 8192, R, C); const int Rb = Epi::PERM ? ((R & ~31) + perm32(R & 31)) : R;
;         voffA[i] = A_TILED ? (unsigned)(R * BK + C) * 2u : (unsigned)(R * K + C) * 2u; voffB[i] = (unsigned)(Rb * BK + C) * 2u; }
;     const size_t kstep = A_TILED ? (size_t)BM * BK * 2 : (size_t)(BK * 2);
;     const size_t hstep = A_TILED ? (size_t)HALF * BK * 2 : (size_t)HALF * K * 2;
;     const size_t tstep = (size_t)BM * K * 2;
;     const size_t kstepB = (size_t)BM * BK * 2, hstepB = (size_t)HALF * BK * 2;
;     const unsigned ldsw = (unsigned)wid * 1024u;
;     const int aoff = lds_byte(wr * 64 + fr, fq * 8), boff = lds_byte(wc * 32 + fr, fq * 8);
;     ...
;     Unit cur, nxt; int ui = 0;
;     if (!S.next(0, cur)) return;
;     acc_t acc[2][2][4][2];
; #pragma unroll
;     for (int a = 0; a < 2; ++a)
; #pragma unroll
;         for (int b = 0; b < 2; ++b)
; #pragma unroll
;             for (int m = 0; m < 4; ++m)
; #pragma unroll
;                 for (int n = 0; n < 2; ++n) acc[a][b][m][n] = acc_t{};
;     frag_t At[4][2], B0[2][2], B1[2][2];
;     const char* cA = (const char*)g.A + (size_t)cur.pm * tstep; const char* cB = (const char*)g.Bt + (size_t)cur.pn * tstep;
;     S.a_ready(cur);
;     if constexpr (SP2) {
;         PG8_STAGE(PG8_SB(0, 0), cB, voffB); PG8_STAGE(PG8_SB(0, 1), cB + hstepB, voffB); PG8_STAGE(PG8_SA(0, 0), cA, voffA); PG8_STAGE(PG8_SA(0, 1), cA + hstep, voffA);
;         if (wr == 1) PG8_BAR;
;         PG8_WAIT_V(2); PG8_BAR;
;         PG8_STAGE(PG8_SB(1, 0), cB + kstepB, voffB); PG8_STAGE(PG8_SA(1, 0), cA + kstep, voffA); PG8_STAGE(PG8_SB(1, 1), cB + hstepB + kstepB, voffB);
.LBB0_1130:
	s_and_b64 vcc, exec, s[4:5]
	v_readfirstlane_b32 s12, v70
	s_cbranch_vccnz .LBB0_1146
	s_waitcnt lgkmcnt(0)
	v_lshlrev_b32_e32 v1, 4, v70
	v_add_u32_e32 v2, 0x2000, v1
	v_ashrrev_i32_e32 v3, 31, v2
	v_lshrrev_b32_e32 v3, 22, v3
	v_add_u32_e32 v3, v2, v3
	s_waitcnt vmcnt(0)
	v_ashrrev_i32_e32 v6, 10, v3
	v_mul_i32_i24_e32 v3, 0x400, v6
	v_sub_u32_e32 v2, v2, v3
	v_lshrrev_b32_e32 v3, 4, v2
	v_bitop3_b32 v2, v3, v2, 32 bitop3:0x6c
	s_ashr_i32 s13, s12, 6
	v_ashrrev_i32_e32 v3, 31, v2
	s_ashr_i32 s5, s12, 8
	s_lshl_b32 s31, s13, 10
	s_mul_i32 s6, s26, 0x2c00000
	v_lshrrev_b32_e32 v3, 26, v3
	s_mul_hi_i32 s4, s26, 0x2c00000
	s_add_u32 s6, s10, s6
	v_add_u32_e32 v3, v2, v3
	v_lshlrev_b32_e32 v4, 3, v6
	s_addc_u32 s4, s11, s4
	v_ashrrev_i32_e32 v7, 6, v3
	v_and_b32_e32 v4, -16, v4
	s_add_u32 s34, s6, 0x800000
	v_add_u32_e32 v4, v7, v4
	s_addc_u32 s35, s4, 0
	v_and_b32_e32 v5, 3, v7
	s_mov_b32 s4, 0x1ffffe0
	v_lshrrev_b32_e32 v8, 2, v4
	v_lshlrev_b32_e32 v9, 1, v4
	v_and_b32_e32 v3, 0xc0, v3
	v_and_or_b32 v5, v4, s4, v5
	v_and_b32_e32 v8, 4, v8
	v_and_b32_e32 v9, 24, v9
	v_sub_u32_e32 v2, v2, v3
	v_or3_b32 v5, v5, v8, v9
	v_lshlrev_b32_e32 v8, 5, v6
	v_ashrrev_i16_sdwa v2, v194, sext(v2) dst_sel:DWORD dst_unused:UNUSED_PAD src0_sel:DWORD src1_sel:BYTE_0
	v_and_b32_e32 v9, 32, v8
	v_bfe_i32 v8, v2, 0, 16
	v_add_lshl_u32 v2, v9, v8, 1
	v_lshl_add_u32 v130, v5, 7, v2
	v_lshl_add_u32 v132, v4, 11, v2
	v_bfe_i32 v2, v70, 27, 1
	v_lshrrev_b32_e32 v2, 22, v2
	v_add_u32_e32 v2, v1, v2
	v_and_b32_e32 v2, 0xfffffc00, v2
	v_sub_u32_e32 v1, v1, v2
	v_lshrrev_b32_e32 v2, 4, v1
	v_ashrrev_i32_e32 v3, 31, v70
	v_bitop3_b32 v1, v2, v1, 32 bitop3:0x6c
	v_lshrrev_b32_e32 v3, 26, v3
	v_ashrrev_i32_e32 v2, 31, v1
	v_add_u32_e32 v3, v70, v3
	v_lshrrev_b32_e32 v2, 26, v2
	v_ashrrev_i32_e32 v10, 6, v3
	v_add_u32_e32 v2, v1, v2
	v_lshlrev_b32_e32 v3, 3, v10
	v_ashrrev_i32_e32 v9, 6, v2
	v_and_b32_e32 v3, -16, v3
	v_add_u32_e32 v3, v9, v3
	v_and_b32_e32 v4, 3, v9
	v_and_or_b32 v4, v3, s4, v4
	v_readlane_b32 s7, v254, 3
	s_nop 1
	s_cmp_lg_u32 s7, 0x100
	s_mov_b32 s7, s28
	s_cbranch_scc1 .LrevG_0
	s_add_i32 s7, s28, 0xa00

; #define PG8_STAGE(bufoff, gbase, voff) do { _Pragma("unroll") for (int _i = 0; _i < 2; ++_i) \
;         __builtin_amdgcn_global_load_lds((const unsigned*)((const char*)(gbase) + (voff)[_i]), (PG8_LAS unsigned*)(lds + (bufoff) + ldsw + _i * 8192), 16, 0, 0); } while (0)
; #define PG8_WAIT_V(n) asm volatile("s_waitcnt vmcnt(" #n ")" ::: "memory")
; #define PG8_BAR __builtin_amdgcn_s_barrier()
;     ...
;         PG8_STAGE(PG8_SB(1, 0), cB + kstepB, voffB); PG8_STAGE(PG8_SA(1, 0), cA + kstep, voffA); PG8_STAGE(PG8_SB(1, 1), cB + hstepB + kstepB, voffB);
;         PG8_WAIT_V(6); PG8_BAR;
;     __device__ __forceinline__ void operator()(const i32x4 (&acc)[2][2][4][2], const pg8::Unit& u, int wr, int wc, int fr_, int fq_, int tid) {
;     ...
;         const float* cp = cmax + u.pn * 256 + wc * 32 + 8 * fq;
;         f32x4 cs[2][2];
;         cs[0][0] = *(const f32x4*)(cp) * (1.0f / 127.0f); cs[0][1] = *(const f32x4*)(cp + 4) * (1.0f / 127.0f);
;         cs[1][0] = *(const f32x4*)(cp + 128) * (1.0f / 127.0f); cs[1][1] = *(const f32x4*)(cp + 132) * (1.0f / 127.0f);
.LBB0_1133:
	s_add_u32 s8, s10, 0x2d800000
	s_addc_u32 s9, s11, 0
	s_mul_hi_i32 s14, s26, 0xb000
	s_mul_i32 s26, s26, 0xb000
	s_add_u32 s15, s10, s26
	s_addc_u32 s14, s11, s14
	s_lshl_b32 s10, s13, 5
	s_and_b32 s41, s10, 0x60
	s_lshl_b32 s40, s5, 6
	s_lshl_b32 s16, s5, 13
	s_lshl_b32 s13, s41, 7
	s_add_u32 s10, s22, 0x8000
	v_mov_b32_e32 v135, v163
	s_addc_u32 s11, s23, 0
	v_mov_b32_e32 v131, v163
	s_add_i32 m0, s36, 0x18000
	v_lshl_add_u64 v[12:13], s[10:11], 0, v[134:135]
	s_waitcnt vmcnt(2)
	s_barrier
	global_load_lds_dwordx4 v[12:13], off
	v_lshl_add_u64 v[12:13], s[10:11], 0, v[130:131]
	s_add_i32 m0, s36, 0x1a000
	s_add_i32 s42, s36, 0x8000
	s_add_i32 s43, s36, 0xa000
	global_load_lds_dwordx4 v[12:13], off
	v_lshl_add_u64 v[2:3], v[2:3], 0, s[78:79]
	s_mov_b32 m0, s42
	s_add_u32 s10, s22, 0xc000
	global_load_lds_dwordx4 v[2:3], off
	v_lshl_add_u64 v[2:3], v[4:5], 0, s[78:79]
	s_mov_b32 m0, s43
	s_addc_u32 s11, s23, 0
	global_load_lds_dwordx4 v[2:3], off
	s_add_i32 m0, s36, 0x1c000
	v_lshl_add_u64 v[2:3], s[10:11], 0, v[134:135]
	global_load_lds_dwordx4 v[2:3], off
	v_lshl_add_u64 v[2:3], s[10:11], 0, v[130:131]
	s_add_i32 m0, s36, 0x1e000
	v_bfe_u32 v155, v70, 4, 2
	global_load_lds_dwordx4 v[2:3], off
	v_and_b32_e32 v1, 15, v70
	v_lshlrev_b32_e32 v2, 4, v155
	v_lshlrev_b32_e32 v3, 2, v70
	v_lshl_or_b32 v2, v1, 6, v2
	v_and_b32_e32 v3, 32, v3
	v_bitop3_b32 v4, v2, s16, v3 bitop3:0xde
	v_bitop3_b32 v158, s13, v2, v3 bitop3:0xf6
	v_lshlrev_b32_e32 v2, 14, v10
	s_cmpk_lt_u32 s12, 0x100
	v_and_b32_e32 v2, 0xffff8000, v2
	s_sext_i32_i16 s21, s4
	s_cselect_b64 s[10:11], -1, 0
	s_ashr_i32 s44, s29, 31
	s_lshl_b32 s4, s41, 2
	v_lshl_add_u32 v2, v9, 11, v2
	v_and_b32_e32 v3, 1, v10
	s_add_u32 s4, s15, s4
	v_lshl_or_b32 v2, v3, 6, v2
	s_addc_u32 s12, s14, 0
	v_lshl_add_u32 v138, v11, 1, v2
	v_lshlrev_b32_e32 v2, 14, v6
	s_add_u32 s45, s4, 0x80000
	v_and_b32_e32 v2, 0xffff8000, v2
	s_waitcnt vmcnt(6)
	s_addc_u32 s46, s12, 0
	s_lshl_b32 s4, s5, 8
	v_lshl_add_u32 v2, v7, 11, v2
	v_and_b32_e32 v3, 1, v6
	s_add_i32 s47, s4, 0
	v_lshl_or_b32 v2, v3, 6, v2
	s_add_i32 s47, s47, 0x20400
	v_mov_b32_e32 v139, v163
	v_lshl_add_u32 v140, v8, 1, v2
	v_mov_b32_e32 v141, v163
	s_mov_b32 s48, 0
	v_add_u32_e32 v159, 0, v4
	v_and_b32_e32 v216, 31, v195
	v_lshrrev_b32_e32 v217, 5, v195
	v_lshl_add_u32 v216, v217, 7, v216
	v_lshlrev_b32_e32 v216, 2, v216
	s_and_b32 s96, s21, 3
	s_lshl_b32 s96, s96, 10
	s_add_u32 s100, s45, s96
	s_addc_u32 s101, s46, 0
	global_load_dword v220, v216, s[100:101]
	s_add_u32 s100, s100, 0x1000
	s_addc_u32 s101, s101, 0
	global_load_dword v221, v216, s[100:101]
	s_add_u32 s100, s100, 0x1000
	s_addc_u32 s101, s101, 0
	global_load_dword v222, v216, s[100:101]
	s_add_u32 s100, s100, 0x1000
	s_addc_u32 s101, s101, 0
	global_load_dword v223, v216, s[100:101]
	s_add_u32 s100, s100, 0x1000
	s_addc_u32 s101, s101, 0
	global_load_dword v224, v216, s[100:101]
	s_add_u32 s100, s100, 0x1000
	s_addc_u32 s101, s101, 0
	global_load_dword v225, v216, s[100:101]
	s_add_u32 s100, s100, 0x1000
	s_addc_u32 s101, s101, 0
	global_load_dword v226, v216, s[100:101]
	s_add_u32 s100, s100, 0x1000
	s_addc_u32 s101, s101, 0
	global_load_dword v227, v216, s[100:101]
	s_add_u32 s100, s100, 0x1000
	s_addc_u32 s101, s101, 0
	global_load_dword v228, v216, s[100:101]
	s_add_u32 s100, s100, 0x1000
	s_addc_u32 s101, s101, 0
	global_load_dword v229, v216, s[100:101]
	s_add_u32 s100, s100, 0x1000
	s_addc_u32 s101, s101, 0
	global_load_dword v230, v216, s[100:101]
	s_lshl_b32 s96, s41, 3
	s_add_i32 s96, s96, 0x21000
	v_lshl_add_u32 v217, v195, 2, s96
	s_waitcnt vmcnt(0)
	v_mul_f32_e32 v220, s76, v220
	v_mul_f32_e32 v221, s76, v221
	v_mul_f32_e32 v222, s76, v222
	v_mul_f32_e32 v223, s76, v223
	v_mul_f32_e32 v224, s76, v224
	v_mul_f32_e32 v225, s76, v225
	v_mul_f32_e32 v226, s76, v226
	v_mul_f32_e32 v227, s76, v227
	v_mul_f32_e32 v228, s76, v228
	v_mul_f32_e32 v229, s76, v229
	v_mul_f32_e32 v230, s76, v230
	ds_write_b32 v217, v220
	ds_write_b32 v217, v221 offset:1024
	ds_write_b32 v217, v222 offset:2048
	ds_write_b32 v217, v223 offset:3072
	ds_write_b32 v217, v224 offset:4096
	ds_write_b32 v217, v225 offset:5120
	ds_write_b32 v217, v226 offset:6144
	ds_write_b32 v217, v227 offset:7168
	ds_write_b32 v217, v228 offset:8192
	ds_write_b32 v217, v229 offset:9216
	ds_write_b32 v217, v230 offset:10240
	s_waitcnt lgkmcnt(0)
	s_barrier
	s_branch .LBB0_1136
